# P0 S5 table job: the twelve loop-parameter loads issued together after loop 1 (two round trips instead of five, not in the start-of-kernel burst), stacked on v93
# baseline (speedup 1.0000x reference)
.LBB0_13:
	v_cvt_f32_u32_e32 v13, v7
	v_cvt_f64_u32_e32 v[10:11], v7
	v_mul_f64 v[10:11], v[2:3], v[10:11]
	v_mul_f64 v[10:11], v[10:11], v[4:5]
	v_mul_f64 v[14:15], v[10:11], s[30:31]
	v_mul_f32_e32 v13, v12, v13
	v_rndne_f64_e32 v[14:15], v[14:15]
	s_waitcnt vmcnt(0)
	v_mul_f32_e32 v13, v6, v13
	v_fma_f64 v[10:11], v[10:11], s[30:31], -v[14:15]
	v_cvt_f32_f64_e32 v11, v[10:11]
	v_mul_f32_e32 v10, 0x3fb8aa3b, v13
	v_exp_f32_e32 v10, v10
	v_cos_f32_e32 v14, v11
	v_sin_f32_e32 v15, v11
	v_add_u32_e32 v9, 0x200, v9
	s_movk_i32 s2, 0x23f
	v_cmp_lt_u32_e32 vcc, s2, v9
	v_pk_mul_f32 v[10:11], v[10:11], v[14:15] op_sel_hi:[0,1]
	v_add_u32_e32 v7, 8, v7
	s_or_b64 s[36:37], vcc, s[36:37]
	ds_write_b64 v8, v[10:11]
	v_add_u32_e32 v8, 0x1000, v8
	s_andn2_b64 exec, exec, s[36:37]
	s_cbranch_execnz .LBB0_13
	s_or_b64 exec, exec, s[36:37]
	s_lshl_b64 s[36:37], s[84:85], 12
	v_lshl_add_u64 v[4:5], v[64:65], 0, s[36:37]
	v_lshl_add_u64 v[6:7], v[68:69], 0, s[36:37]
	v_lshl_add_u64 v[8:9], v[70:71], 0, s[4:5]
	v_lshl_add_u64 v[10:11], v[72:73], 0, s[4:5]
	s_mov_b64 s[4:5], 0
	v_mov_b32_e32 v13, v88
	v_mov_b32_e32 v14, v90
	global_load_dword v220, v[10:11], off
	global_load_dword v221, v[8:9], off
	global_load_dword v222, v[6:7], off
	global_load_dword v223, v[4:5], off
	v_lshl_add_u64 v[232:233], v[4:5], 0, s[34:35]
	v_lshl_add_u64 v[234:235], v[6:7], 0, s[34:35]
	v_lshl_add_u64 v[236:237], v[8:9], 0, s[72:73]
	v_lshl_add_u64 v[238:239], v[10:11], 0, s[72:73]
	global_load_dword v224, v[238:239], off
	global_load_dword v225, v[236:237], off
	global_load_dword v226, v[234:235], off
	global_load_dword v227, v[232:233], off
	v_lshl_add_u64 v[232:233], v[74:75], 0, s[36:37]
	v_lshl_add_u64 v[234:235], v[76:77], 0, s[36:37]
	global_load_dword v228, v[232:233], off
	global_load_dword v229, v[234:235], off
	v_lshl_add_u64 v[232:233], v[232:233], 0, s[34:35]
	v_lshl_add_u64 v[234:235], v[234:235], 0, s[34:35]
	global_load_dword v230, v[232:233], off
	global_load_dword v231, v[234:235], off
	s_waitcnt vmcnt(0)

.LBB0_122:
	v_cvt_f32_u32_e32 v13, v7
	v_cvt_f64_u32_e32 v[10:11], v7
	v_mul_f64 v[10:11], v[2:3], v[10:11]
	v_mul_f64 v[10:11], v[10:11], v[4:5]
	v_mul_f64 v[14:15], v[10:11], s[24:25]
	v_mul_f32_e32 v13, v12, v13
	v_rndne_f64_e32 v[14:15], v[14:15]
	s_waitcnt vmcnt(0)
	v_mul_f32_e32 v13, v6, v13
	v_fma_f64 v[10:11], v[10:11], s[24:25], -v[14:15]
	v_cvt_f32_f64_e32 v11, v[10:11]
	v_mul_f32_e32 v10, 0x3fb8aa3b, v13
	v_exp_f32_e32 v10, v10
	v_cos_f32_e32 v14, v11
	v_sin_f32_e32 v15, v11
	v_add_u32_e32 v9, 0x200, v9
	s_movk_i32 s2, 0x23f
	v_cmp_lt_u32_e32 vcc, s2, v9
	v_pk_mul_f32 v[10:11], v[10:11], v[14:15] op_sel_hi:[0,1]
	v_add_u32_e32 v7, 8, v7
	s_or_b64 s[38:39], vcc, s[38:39]
	ds_write_b64 v8, v[10:11]
	v_add_u32_e32 v8, 0x1000, v8
	s_andn2_b64 exec, exec, s[38:39]
	s_cbranch_execnz .LBB0_122
	s_or_b64 exec, exec, s[38:39]
	s_lshl_b64 s[38:39], s[36:37], 12
	v_lshl_add_u64 v[4:5], v[64:65], 0, s[38:39]
	v_lshl_add_u64 v[6:7], v[68:69], 0, s[38:39]
	v_lshl_add_u64 v[8:9], v[70:71], 0, s[4:5]
	v_lshl_add_u64 v[10:11], v[72:73], 0, s[4:5]
	s_mov_b64 s[4:5], 0
	v_mov_b32_e32 v13, v88
	v_mov_b32_e32 v14, v91
	global_load_dword v220, v[10:11], off
	global_load_dword v221, v[8:9], off
	global_load_dword v222, v[6:7], off
	global_load_dword v223, v[4:5], off
	v_lshl_add_u64 v[232:233], v[4:5], 0, s[26:27]
	v_lshl_add_u64 v[234:235], v[6:7], 0, s[26:27]
	v_lshl_add_u64 v[236:237], v[8:9], 0, s[28:29]
	v_lshl_add_u64 v[238:239], v[10:11], 0, s[28:29]
	global_load_dword v224, v[238:239], off
	global_load_dword v225, v[236:237], off
	global_load_dword v226, v[234:235], off
	global_load_dword v227, v[232:233], off
	v_lshl_add_u64 v[232:233], v[74:75], 0, s[38:39]
	v_lshl_add_u64 v[234:235], v[76:77], 0, s[38:39]
	global_load_dword v228, v[232:233], off
	global_load_dword v229, v[234:235], off
	v_lshl_add_u64 v[232:233], v[232:233], 0, s[26:27]
	v_lshl_add_u64 v[234:235], v[234:235], 0, s[26:27]
	global_load_dword v230, v[232:233], off
	global_load_dword v231, v[234:235], off
	s_waitcnt vmcnt(0)
